# shared GEMM routine: the next tile's first two K slabs (tile map, ring-release barrier, LDS-DMA) are issued before the current tile's epilogue, for all six GEMM sites
# baseline (speedup 1.0000x reference)
; DI int get_tid() { int t = threadIdx.x; asm volatile("" : "+v"(t)); return t; }
; DI void tile_map(int t, int MT, int NT, int& mt, int& nt) {
;   const int xc = t & 7, j = t >> 3, mtx = MT >> 3, full = NT >> 3, per = mtx * 8;
;   int sc = j / per, rem, w;
;   if (sc < full) { rem = j - sc * per; w = 8; }
;   else { sc = full; rem = j - full * per; w = NT & 7; }
;   const int m = rem / w, nn = rem - m * w;
;   mt = xc * mtx + m; nt = sc * 8 + nn;
; }
; template <int EPI>
; DI void gemm_phase(const Params& p, int layer, const bf16_t* __restrict__ A, int lda, const bf16_t* __restrict__ Bt, int ldb, int K, int MT, int NT,
;                    char* smem, bool rev = false) {
;     ...
;   const int tid = get_tid(), lane = tid & 63, wave = tid >> 6, wr = wave >> 1, wc = wave & 1;
;   const int total = MT * NT;
;   int t = rev ? (int)(gridDim.x - 1 - blockIdx.x) : (int)blockIdx.x;
;   if (t >= total) return;
;   uint4 pa0, pa1, pa2, pa3, pb0, pb1, pb2, pb3, qa0, qa1, qa2, qa3, qb0, qb1, qb2, qb3;
;   const int lr = tid >> 3, lc = (tid & 7) * 8;
;   const int nk = K >> 6;
;   const int soff = lr * LDT + lc;
;   const int aoff = (wr * 64 + (lane & 31)) * LDT + (lane >> 5) * 8;
;   const int boff = (wc * 64 + (lane & 31)) * LDT + (lane >> 5) * 8;
;   int mt, nt; tile_map(t, MT, NT, mt, nt);
;   int m0 = mt * 128, n0 = nt * 128;
;   const bf16_t* Agl = A + (size_t)(m0 + lr) * lda + lc;
;   const bf16_t* Bgl = Bt + (size_t)(n0 + lr) * ldb + lc;
.Lmg_pare_9:
	s_lshl_b32 s0, s61, 3
	s_mul_i32 s64, s0, s62
	v_lshrrev_b32_e32 v184, 2, v140
	v_and_b32_e32 v185, 3, v140
	v_bfe_u32 v186, v140, 4, 2
	v_xor_b32_e32 v185, v185, v186
	v_lshlrev_b32_e32 v185, 4, v185
	s_lshl_b32 s0, s77, 6
	v_add_u32_e32 v186, s0, v184
	v_mul_lo_u32 v186, v186, s58
	v_add_u32_e32 v213, v186, v185
	s_lshl_b32 s0, s58, 4
	s_sub_u32 s0, s0, 0x400
	v_add_u32_e32 v214, s0, v213
	v_add_u32_e32 v215, s0, v214
	v_add_u32_e32 v216, s0, v215
	s_lshl_b32 s0, s77, 5
	v_add_u32_e32 v186, s0, v184
	v_mul_lo_u32 v186, v186, s59
	v_add_u32_e32 v217, v186, v185
	s_lshl_b32 s0, s59, 4
	s_sub_u32 s0, s0, 0x400
	v_add_u32_e32 v218, s0, v217
	v_bfe_u32 v184, v140, 2, 2
	v_xor_b32_e32 v185, v184, v228
	v_xor_b32_e32 v186, 2, v185
	v_lshlrev_b32_e32 v187, 6, v227
	v_lshl_add_u32 v185, v185, 4, v187
	v_lshl_add_u32 v186, v186, 4, v187
	s_mul_i32 s0, s78, 0x3000
	v_add_u32_e32 v219, s0, v185
	v_add_u32_e32 v220, s0, v186
	s_mul_i32 s0, s79, 0x3000
	s_add_u32 s0, s0, 0x1000
	v_add_u32_e32 v221, s0, v185
	v_add_u32_e32 v222, s0, v186
	s_cmp_ge_u32 s66, s64
	s_cbranch_scc1 .Lmg_done
	s_and_b32 s0, s66, 7
	s_lshr_b32 s1, s66, 3
	s_lshr_b32 s10, s1, 3
	s_mul_i32 s10, s10, s63
	s_lshr_b32 s10, s10, 16
	s_lshr_b32 s11, s62, 3
	s_mov_b32 s12, 8
	s_mov_b32 s13, 0x2000
	s_cmp_ge_u32 s10, s11
	s_cbranch_scc0 .Lmg_tm_10
	s_mov_b32 s10, s11
	s_and_b32 s12, s62, 7
	s_mov_b32 s13, s69

; template <int EPI>
; DI void gemm_phase(const Params& p, int layer, const bf16_t* __restrict__ A, int lda, const bf16_t* __restrict__ Bt, int ldb, int K, int MT, int NT,
;                    char* smem, bool rev = false) {
;     ...
;   G_LOAD(p, 0)
;   G_LOAD(q, 64)
;   for (;;) {
;     G_WRITE(p, 0)
;     __syncthreads();
;     if (nk > 2) G_LOAD(p, 128)
;     f32x16 acc[2][2];
; #pragma unroll
;     for (int i = 0; i < 2; ++i)
; #pragma unroll
;       for (int j = 0; j < 2; ++j)
; #pragma unroll
;         for (int r = 0; r < 16; ++r) acc[i][j][r] = 0.f;
;     for (int kt = 0; kt < nk; kt += 2) {
;       G_COMPUTE(0)
;       G_WRITE(q, 1)
;       __syncthreads();
;       if (kt + 3 < nk) G_LOAD(q, (kt + 3) << 6)
;       G_COMPUTE(1)
;       if (kt + 2 < nk) G_WRITE(p, 0)
;       __syncthreads();
;       if (kt + 4 < nk) G_LOAD(p, (kt + 4) << 6)
;     }
.Lmg_tile:
	s_mov_b32 s75, 0
	v_mov_b32_e32 v223, v219
	v_mov_b32_e32 v225, v221
	v_mov_b32_e32 v224, v220
	v_mov_b32_e32 v226, v222
	s_sub_u32 s76, s60, 3
	s_waitcnt vmcnt(6)
	s_barrier
	ds_read_b128 v[128:131], v225
	ds_read_b128 v[132:135], v225 offset:6144
	ds_read_b128 v[144:147], v223
	ds_read_b128 v[148:151], v223 offset:2048
	ds_read_b128 v[152:155], v223 offset:6144
	ds_read_b128 v[156:159], v223 offset:8192
	ds_read_b128 v[160:163], v226
	ds_read_b128 v[164:167], v226 offset:6144
	ds_read_b128 v[168:171], v224
	ds_read_b128 v[172:175], v224 offset:2048
	ds_read_b128 v[176:179], v224 offset:6144
	ds_read_b128 v[180:183], v224 offset:8192
	s_add_u32 s75, s75, 0x6000
	s_cmp_eq_u32 s75, 0x12000
	s_cselect_b32 s75, 0, s75
	s_mov_b32 m0, s74
	s_waitcnt lgkmcnt(9)
	v_mfma_f32_32x32x16_bf16 v[0:15], v[144:147], v[128:131], 0
	v_mfma_f32_32x32x16_bf16 v[16:31], v[144:147], v[132:135], 0
	global_load_lds_dwordx4 v213, s[70:71] offset:0
	s_waitcnt lgkmcnt(8)
	v_mfma_f32_32x32x16_bf16 v[32:47], v[148:151], v[128:131], 0
	v_mfma_f32_32x32x16_bf16 v[48:63], v[148:151], v[132:135], 0
	global_load_lds_dwordx4 v214, s[70:71] offset:1024
	s_waitcnt lgkmcnt(7)
	v_mfma_f32_32x32x16_bf16 v[64:79], v[152:155], v[128:131], 0
	v_mfma_f32_32x32x16_bf16 v[80:95], v[152:155], v[132:135], 0
	global_load_lds_dwordx4 v215, s[70:71] offset:2048
	s_waitcnt lgkmcnt(6)
	v_mfma_f32_32x32x16_bf16 v[96:111], v[156:159], v[128:131], 0
	v_mfma_f32_32x32x16_bf16 v[112:127], v[156:159], v[132:135], 0
	global_load_lds_dwordx4 v216, s[70:71] offset:3072
	s_add_u32 m0, s74, 0x1000
	s_waitcnt lgkmcnt(3)
	v_mfma_f32_32x32x16_bf16 v[0:15], v[168:171], v[160:163], v[0:15]
	v_mfma_f32_32x32x16_bf16 v[16:31], v[168:171], v[164:167], v[16:31]
	global_load_lds_dwordx4 v217, s[72:73] offset:0
	s_waitcnt lgkmcnt(2)
	v_mfma_f32_32x32x16_bf16 v[32:47], v[172:175], v[160:163], v[32:47]
	v_mfma_f32_32x32x16_bf16 v[48:63], v[172:175], v[164:167], v[48:63]
	global_load_lds_dwordx4 v218, s[72:73] offset:1024
	s_add_u32 s70, s70, s81
	s_addc_u32 s71, s71, 0
	s_add_u32 s72, s72, s48
	s_addc_u32 s73, s73, 0
	s_waitcnt lgkmcnt(1)
	v_mfma_f32_32x32x16_bf16 v[64:79], v[176:179], v[160:163], v[64:79]
	v_mfma_f32_32x32x16_bf16 v[80:95], v[176:179], v[164:167], v[80:95]
	v_add_u32_e32 v223, s75, v219
	v_add_u32_e32 v225, s75, v221
	v_add_u32_e32 v224, s75, v220
	v_add_u32_e32 v226, s75, v222
	s_waitcnt lgkmcnt(0)
	v_mfma_f32_32x32x16_bf16 v[96:111], v[180:183], v[160:163], v[96:111]
	v_mfma_f32_32x32x16_bf16 v[112:127], v[180:183], v[164:167], v[112:127]
	s_add_u32 s74, s74, 0x6000
	s_sub_u32 s1, s74, 0x12000
	s_add_u32 s0, s80, 0x12000
	s_cmp_ge_u32 s74, s0
	s_cselect_b32 s74, s1, s74
.Lmg_kloop:
	s_waitcnt vmcnt(6)
	s_barrier
	ds_read_b128 v[128:131], v225
	ds_read_b128 v[132:135], v225 offset:6144
	ds_read_b128 v[144:147], v223
	ds_read_b128 v[148:151], v223 offset:2048
	ds_read_b128 v[152:155], v223 offset:6144
	ds_read_b128 v[156:159], v223 offset:8192
	ds_read_b128 v[160:163], v226
	ds_read_b128 v[164:167], v226 offset:6144
	ds_read_b128 v[168:171], v224
	ds_read_b128 v[172:175], v224 offset:2048
	ds_read_b128 v[176:179], v224 offset:6144
	ds_read_b128 v[180:183], v224 offset:8192
	s_add_u32 s75, s75, 0x6000
	s_cmp_eq_u32 s75, 0x12000
	s_cselect_b32 s75, 0, s75
	s_mov_b32 m0, s74
	s_waitcnt lgkmcnt(9)
	v_mfma_f32_32x32x16_bf16 v[0:15], v[144:147], v[128:131], v[0:15]
	v_mfma_f32_32x32x16_bf16 v[16:31], v[144:147], v[132:135], v[16:31]
	global_load_lds_dwordx4 v213, s[70:71] offset:0
	s_waitcnt lgkmcnt(8)
	v_mfma_f32_32x32x16_bf16 v[32:47], v[148:151], v[128:131], v[32:47]
	v_mfma_f32_32x32x16_bf16 v[48:63], v[148:151], v[132:135], v[48:63]
	global_load_lds_dwordx4 v214, s[70:71] offset:1024
	s_waitcnt lgkmcnt(7)
	v_mfma_f32_32x32x16_bf16 v[64:79], v[152:155], v[128:131], v[64:79]
	v_mfma_f32_32x32x16_bf16 v[80:95], v[152:155], v[132:135], v[80:95]
	global_load_lds_dwordx4 v215, s[70:71] offset:2048
	s_waitcnt lgkmcnt(6)
	v_mfma_f32_32x32x16_bf16 v[96:111], v[156:159], v[128:131], v[96:111]
	v_mfma_f32_32x32x16_bf16 v[112:127], v[156:159], v[132:135], v[112:127]
	global_load_lds_dwordx4 v216, s[70:71] offset:3072
	s_add_u32 m0, s74, 0x1000
	s_waitcnt lgkmcnt(3)
	v_mfma_f32_32x32x16_bf16 v[0:15], v[168:171], v[160:163], v[0:15]
	v_mfma_f32_32x32x16_bf16 v[16:31], v[168:171], v[164:167], v[16:31]
	global_load_lds_dwordx4 v217, s[72:73] offset:0
	s_waitcnt lgkmcnt(2)
	v_mfma_f32_32x32x16_bf16 v[32:47], v[172:175], v[160:163], v[32:47]
	v_mfma_f32_32x32x16_bf16 v[48:63], v[172:175], v[164:167], v[48:63]
	global_load_lds_dwordx4 v218, s[72:73] offset:1024
	s_add_u32 s70, s70, s81
	s_addc_u32 s71, s71, 0
	s_add_u32 s72, s72, s48
	s_addc_u32 s73, s73, 0
	s_waitcnt lgkmcnt(1)
	v_mfma_f32_32x32x16_bf16 v[64:79], v[176:179], v[160:163], v[64:79]
	v_mfma_f32_32x32x16_bf16 v[80:95], v[176:179], v[164:167], v[80:95]
	v_add_u32_e32 v223, s75, v219
	v_add_u32_e32 v225, s75, v221
	v_add_u32_e32 v224, s75, v220
	v_add_u32_e32 v226, s75, v222
	s_waitcnt lgkmcnt(0)
	v_mfma_f32_32x32x16_bf16 v[96:111], v[180:183], v[160:163], v[96:111]
	v_mfma_f32_32x32x16_bf16 v[112:127], v[180:183], v[164:167], v[112:127]
	s_add_u32 s74, s74, 0x6000
	s_sub_u32 s1, s74, 0x12000
	s_add_u32 s0, s80, 0x12000
	s_cmp_ge_u32 s74, s0
	s_cselect_b32 s74, s1, s74
	s_sub_u32 s76, s76, 1
	s_cmp_lg_u32 s76, 0
	s_cbranch_scc1 .Lmg_kloop
; template <int EPI>
; DI void gemm_phase(const Params& p, int layer, const bf16_t* __restrict__ A, int lda, const bf16_t* __restrict__ Bt, int ldb, int K, int MT, int NT,
;                    char* smem, bool rev = false) {
;     ...
;     for (int kt = 0; kt < nk; kt += 2) {
;       G_COMPUTE(0)
;       G_WRITE(q, 1)
;       __syncthreads();
;       if (kt + 3 < nk) G_LOAD(q, (kt + 3) << 6)
;       G_COMPUTE(1)
;       if (kt + 2 < nk) G_WRITE(p, 0)
;       __syncthreads();
;       if (kt + 4 < nk) G_LOAD(p, (kt + 4) << 6)
;     }
;     const int tn = t + gridDim.x;
;     const bool has_next = tn < total;
;     const int m0c = m0, n0c = n0;
;     constexpr bool PRE = (EPI != EPI_QUP && EPI != EPI_RES1 && EPI != EPI_RES2);
;     if (has_next) {
;       tile_map(tn, MT, NT, mt, nt);
;       m0 = mt * 128; n0 = nt * 128;
;       Agl = A + (size_t)(m0 + lr) * lda + lc;
;       Bgl = Bt + (size_t)(n0 + lr) * ldb + lc;
;       if (PRE) { G_LOAD(p, 0) G_LOAD(q, 64) }
;     }
	s_waitcnt vmcnt(6)
	s_barrier
	ds_read_b128 v[128:131], v225
	ds_read_b128 v[132:135], v225 offset:6144
	ds_read_b128 v[144:147], v223
	ds_read_b128 v[148:151], v223 offset:2048
	ds_read_b128 v[152:155], v223 offset:6144
	ds_read_b128 v[156:159], v223 offset:8192
	ds_read_b128 v[160:163], v226
	ds_read_b128 v[164:167], v226 offset:6144
	ds_read_b128 v[168:171], v224
	ds_read_b128 v[172:175], v224 offset:2048
	ds_read_b128 v[176:179], v224 offset:6144
	ds_read_b128 v[180:183], v224 offset:8192
	s_add_u32 s75, s75, 0x6000
	s_cmp_eq_u32 s75, 0x12000
	s_cselect_b32 s75, 0, s75
	s_waitcnt lgkmcnt(9)
	v_mfma_f32_32x32x16_bf16 v[0:15], v[144:147], v[128:131], v[0:15]
	v_mfma_f32_32x32x16_bf16 v[16:31], v[144:147], v[132:135], v[16:31]
	s_waitcnt lgkmcnt(8)
	v_mfma_f32_32x32x16_bf16 v[32:47], v[148:151], v[128:131], v[32:47]
	v_mfma_f32_32x32x16_bf16 v[48:63], v[148:151], v[132:135], v[48:63]
	s_waitcnt lgkmcnt(7)
	v_mfma_f32_32x32x16_bf16 v[64:79], v[152:155], v[128:131], v[64:79]
	v_mfma_f32_32x32x16_bf16 v[80:95], v[152:155], v[132:135], v[80:95]
	s_waitcnt lgkmcnt(6)
	v_mfma_f32_32x32x16_bf16 v[96:111], v[156:159], v[128:131], v[96:111]
	v_mfma_f32_32x32x16_bf16 v[112:127], v[156:159], v[132:135], v[112:127]
	s_waitcnt lgkmcnt(3)
	v_mfma_f32_32x32x16_bf16 v[0:15], v[168:171], v[160:163], v[0:15]
	v_mfma_f32_32x32x16_bf16 v[16:31], v[168:171], v[164:167], v[16:31]
	s_waitcnt lgkmcnt(2)
	v_mfma_f32_32x32x16_bf16 v[32:47], v[172:175], v[160:163], v[32:47]
	v_mfma_f32_32x32x16_bf16 v[48:63], v[172:175], v[164:167], v[48:63]
	s_waitcnt lgkmcnt(1)
	v_mfma_f32_32x32x16_bf16 v[64:79], v[176:179], v[160:163], v[64:79]
	v_mfma_f32_32x32x16_bf16 v[80:95], v[176:179], v[164:167], v[80:95]
	v_add_u32_e32 v223, s75, v219
	v_add_u32_e32 v225, s75, v221
	v_add_u32_e32 v224, s75, v220
	v_add_u32_e32 v226, s75, v222
	s_waitcnt lgkmcnt(0)
	v_mfma_f32_32x32x16_bf16 v[96:111], v[180:183], v[160:163], v[96:111]
	v_mfma_f32_32x32x16_bf16 v[112:127], v[180:183], v[164:167], v[112:127]
	s_waitcnt vmcnt(0)
	s_barrier
	ds_read_b128 v[128:131], v225
	ds_read_b128 v[132:135], v225 offset:6144
	ds_read_b128 v[144:147], v223
	ds_read_b128 v[148:151], v223 offset:2048
	ds_read_b128 v[152:155], v223 offset:6144
	ds_read_b128 v[156:159], v223 offset:8192
	ds_read_b128 v[160:163], v226
	ds_read_b128 v[164:167], v226 offset:6144
	ds_read_b128 v[168:171], v224
	ds_read_b128 v[172:175], v224 offset:2048
	ds_read_b128 v[176:179], v224 offset:6144
	ds_read_b128 v[180:183], v224 offset:8192
	s_add_u32 s75, s75, 0x6000
	s_cmp_eq_u32 s75, 0x12000
	s_cselect_b32 s75, 0, s75
	s_waitcnt lgkmcnt(9)
	v_mfma_f32_32x32x16_bf16 v[0:15], v[144:147], v[128:131], v[0:15]
	v_mfma_f32_32x32x16_bf16 v[16:31], v[144:147], v[132:135], v[16:31]
	s_waitcnt lgkmcnt(8)
	v_mfma_f32_32x32x16_bf16 v[32:47], v[148:151], v[128:131], v[32:47]
	v_mfma_f32_32x32x16_bf16 v[48:63], v[148:151], v[132:135], v[48:63]
	s_waitcnt lgkmcnt(7)
	v_mfma_f32_32x32x16_bf16 v[64:79], v[152:155], v[128:131], v[64:79]
	v_mfma_f32_32x32x16_bf16 v[80:95], v[152:155], v[132:135], v[80:95]
	s_waitcnt lgkmcnt(6)
	v_mfma_f32_32x32x16_bf16 v[96:111], v[156:159], v[128:131], v[96:111]
	v_mfma_f32_32x32x16_bf16 v[112:127], v[156:159], v[132:135], v[112:127]
	s_waitcnt lgkmcnt(3)
	v_mfma_f32_32x32x16_bf16 v[0:15], v[168:171], v[160:163], v[0:15]
	v_mfma_f32_32x32x16_bf16 v[16:31], v[168:171], v[164:167], v[16:31]
	s_waitcnt lgkmcnt(2)
	v_mfma_f32_32x32x16_bf16 v[32:47], v[172:175], v[160:163], v[32:47]
	v_mfma_f32_32x32x16_bf16 v[48:63], v[172:175], v[164:167], v[48:63]
	s_waitcnt lgkmcnt(1)
	v_mfma_f32_32x32x16_bf16 v[64:79], v[176:179], v[160:163], v[64:79]
	v_mfma_f32_32x32x16_bf16 v[80:95], v[176:179], v[164:167], v[80:95]
	v_add_u32_e32 v223, s75, v219
	v_add_u32_e32 v225, s75, v221
	v_add_u32_e32 v224, s75, v220
	v_add_u32_e32 v226, s75, v222
	s_waitcnt lgkmcnt(0)
	v_mfma_f32_32x32x16_bf16 v[96:111], v[180:183], v[160:163], v[96:111]
	v_mfma_f32_32x32x16_bf16 v[112:127], v[180:183], v[164:167], v[112:127]
	s_mov_b32 s100, s67
	s_mov_b32 s101, s68
	s_add_u32 s66, s66, s65
	s_cmp_ge_u32 s66, s64
	s_cbranch_scc1 .Lmg_nopre_11
	s_and_b32 s0, s66, 7
	s_lshr_b32 s1, s66, 3
	s_lshr_b32 s10, s1, 3
	s_mul_i32 s10, s10, s63
	s_lshr_b32 s10, s10, 16
	s_lshr_b32 s11, s62, 3
	s_mov_b32 s12, 8
	s_mov_b32 s13, 0x2000
	s_cmp_ge_u32 s10, s11
	s_cbranch_scc0 .Lmg_tm_12
	s_mov_b32 s10, s11
	s_and_b32 s12, s62, 7
	s_mov_b32 s13, s69

; template <int EPI>
; DI void gemm_phase(const Params& p, int layer, const bf16_t* __restrict__ A, int lda, const bf16_t* __restrict__ Bt, int ldb, int K, int MT, int NT,
;                    char* smem, bool rev = false) {
;     ...
;     const int tn = t + gridDim.x;
;     const bool has_next = tn < total;
;     const int m0c = m0, n0c = n0;
;     constexpr bool PRE = (EPI != EPI_QUP && EPI != EPI_RES1 && EPI != EPI_RES2);
;     if (has_next) {
;       tile_map(tn, MT, NT, mt, nt);
;       m0 = mt * 128; n0 = nt * 128;
;       Agl = A + (size_t)(m0 + lr) * lda + lc;
;       Bgl = Bt + (size_t)(n0 + lr) * ldb + lc;
;       if (PRE) { G_LOAD(p, 0) G_LOAD(q, 64) }
;     }
;     epilogue<EPI>(p, layer, acc, m0c + wr * 64, n0c + wc * 64, lane);
.Lmg_nopre_11:
	s_mov_b32 s0, s67
	s_mov_b32 s67, s100
	s_mov_b32 s100, s0
	s_mov_b32 s0, s68
	s_mov_b32 s68, s101
	s_mov_b32 s101, s0

; template <int EPI>
; DI void gemm_phase(const Params& p, int layer, const bf16_t* __restrict__ A, int lda, const bf16_t* __restrict__ Bt, int ldb, int K, int MT, int NT,
;                    char* smem, bool rev = false) {
;     ...
;     if (!has_next) break;
;     if (!PRE) { G_LOAD(p, 0) G_LOAD(q, 64) }
;     t = tn;
;   }
.Lmg_next:
	s_mov_b32 s67, s100
	s_mov_b32 s68, s101
	s_cmp_ge_u32 s66, s64
	s_cbranch_scc1 .Lmg_done
	s_branch .Lmg_tile
